# decode pass 1b: suffix product over key groups as straight-line predicated code (31 LDS reads in two batches) instead of a divergent loop with one LDS round trip per step
# speedup vs baseline: 1.0034x; 1.0013x over previous
; #define LDS_WAIT() asm volatile("s_waitcnt lgkmcnt(0)" ::: "memory")
; __device__ __forceinline__ void decode_item(Frame& F, const Args& a, int l, int item, unsigned char* ws) {
;     ...
;         const int qh = tid & 15, sg = tid >> 4;
;         float pr = 1.f;
; #pragma unroll
;         for (int j = 0; j < 8; ++j) pr *= OM[(sg * 8 + j) * 16 + qh];
;         SEGT[sg * 16 + qh] = pr;
;         LDS_WAIT(); __syncthreads();
;         float suf = 1.f;
.LBB0_1213:
	s_or_b64 exec, exec, s[0:1]
	v_and_b32_e32 v4, 15, v1
	v_ashrrev_i32_e32 v2, 4, v1
	v_lshlrev_b32_e32 v5, 9, v2
	v_lshlrev_b32_e32 v3, 2, v4
	v_add3_u32 v5, 0, v5, v3
	s_waitcnt lgkmcnt(0)
	s_waitcnt lgkmcnt(0)
	s_barrier
	ds_read2_b32 v[6:7], v5 offset1:16
	v_cmp_gt_i32_e32 vcc, 31, v2
	s_waitcnt lgkmcnt(0)
	v_mul_f32_e32 v8, v6, v7
	ds_read2_b32 v[6:7], v5 offset0:32 offset1:48
	s_waitcnt lgkmcnt(0)
	v_mul_f32_e32 v6, v8, v6
	v_mul_f32_e32 v8, v6, v7
	ds_read2_b32 v[6:7], v5 offset0:64 offset1:80
	s_waitcnt lgkmcnt(0)
	v_mul_f32_e32 v6, v8, v6
	v_mul_f32_e32 v8, v6, v7
	ds_read2_b32 v[6:7], v5 offset0:96 offset1:112
	s_waitcnt lgkmcnt(0)
	v_mul_f32_e32 v5, v8, v6
	v_mul_f32_e32 v5, v5, v7
	v_lshl_add_u32 v6, v1, 2, 0
	ds_write_b32 v6, v5 offset:32768
	s_waitcnt lgkmcnt(0)
	v_mov_b32_e32 v5, 1.0
	s_waitcnt lgkmcnt(0)
	s_barrier
	v_readlane_b32 s2, v253, 61
	v_mov_b32_e32 v5, 1.0
	s_nop 1
	v_lshl_add_u32 v4, v4, 2, s2
	s_nop 0
	v_add_u32_e32 v4, 0xfffff880, v4
	ds_read_b32 v184, v4 offset:1920
	ds_read_b32 v185, v4 offset:1856
	ds_read_b32 v186, v4 offset:1792
	ds_read_b32 v187, v4 offset:1728
	ds_read_b32 v188, v4 offset:1664
	ds_read_b32 v189, v4 offset:1600
	ds_read_b32 v190, v4 offset:1536
	ds_read_b32 v191, v4 offset:1472
	ds_read_b32 v192, v4 offset:1408
	ds_read_b32 v193, v4 offset:1344
	ds_read_b32 v194, v4 offset:1280
	ds_read_b32 v195, v4 offset:1216
	ds_read_b32 v196, v4 offset:1152
	ds_read_b32 v197, v4 offset:1088
	ds_read_b32 v198, v4 offset:1024
	ds_read_b32 v199, v4 offset:960
	v_cmp_gt_i32_e32 vcc, 31, v2
	s_waitcnt lgkmcnt(15)
	s_nop 1
	v_cndmask_b32_e32 v184, 1.0, v184, vcc
	v_mul_f32_e32 v5, v5, v184
	v_cmp_gt_i32_e32 vcc, 30, v2
	s_waitcnt lgkmcnt(14)
	s_nop 1
	v_cndmask_b32_e32 v185, 1.0, v185, vcc
	v_mul_f32_e32 v5, v5, v185
	v_cmp_gt_i32_e32 vcc, 29, v2
	s_waitcnt lgkmcnt(13)
	s_nop 1
	v_cndmask_b32_e32 v186, 1.0, v186, vcc
	v_mul_f32_e32 v5, v5, v186
	v_cmp_gt_i32_e32 vcc, 28, v2
	s_waitcnt lgkmcnt(12)
	s_nop 1
	v_cndmask_b32_e32 v187, 1.0, v187, vcc
	v_mul_f32_e32 v5, v5, v187
	v_cmp_gt_i32_e32 vcc, 27, v2
	s_waitcnt lgkmcnt(11)
	s_nop 1
	v_cndmask_b32_e32 v188, 1.0, v188, vcc
	v_mul_f32_e32 v5, v5, v188
	v_cmp_gt_i32_e32 vcc, 26, v2
	s_waitcnt lgkmcnt(10)
	s_nop 1
	v_cndmask_b32_e32 v189, 1.0, v189, vcc
	v_mul_f32_e32 v5, v5, v189
	v_cmp_gt_i32_e32 vcc, 25, v2
	s_waitcnt lgkmcnt(9)
	s_nop 1
	v_cndmask_b32_e32 v190, 1.0, v190, vcc
	v_mul_f32_e32 v5, v5, v190
	v_cmp_gt_i32_e32 vcc, 24, v2
	s_waitcnt lgkmcnt(8)
	s_nop 1
	v_cndmask_b32_e32 v191, 1.0, v191, vcc
	v_mul_f32_e32 v5, v5, v191
	v_cmp_gt_i32_e32 vcc, 23, v2
	s_waitcnt lgkmcnt(7)
	s_nop 1
	v_cndmask_b32_e32 v192, 1.0, v192, vcc
	v_mul_f32_e32 v5, v5, v192
	v_cmp_gt_i32_e32 vcc, 22, v2
	s_waitcnt lgkmcnt(6)
	s_nop 1
	v_cndmask_b32_e32 v193, 1.0, v193, vcc
	v_mul_f32_e32 v5, v5, v193
	v_cmp_gt_i32_e32 vcc, 21, v2
	s_waitcnt lgkmcnt(5)
	s_nop 1
	v_cndmask_b32_e32 v194, 1.0, v194, vcc
	v_mul_f32_e32 v5, v5, v194
	v_cmp_gt_i32_e32 vcc, 20, v2
	s_waitcnt lgkmcnt(4)
	s_nop 1
	v_cndmask_b32_e32 v195, 1.0, v195, vcc
	v_mul_f32_e32 v5, v5, v195
	v_cmp_gt_i32_e32 vcc, 19, v2
	s_waitcnt lgkmcnt(3)
	s_nop 1
	v_cndmask_b32_e32 v196, 1.0, v196, vcc
	v_mul_f32_e32 v5, v5, v196
	v_cmp_gt_i32_e32 vcc, 18, v2
	s_waitcnt lgkmcnt(2)
	s_nop 1
	v_cndmask_b32_e32 v197, 1.0, v197, vcc
	v_mul_f32_e32 v5, v5, v197
	v_cmp_gt_i32_e32 vcc, 17, v2
	s_waitcnt lgkmcnt(1)
	s_nop 1
	v_cndmask_b32_e32 v198, 1.0, v198, vcc
	v_mul_f32_e32 v5, v5, v198
	v_cmp_gt_i32_e32 vcc, 16, v2
	s_waitcnt lgkmcnt(0)
	s_nop 1
	v_cndmask_b32_e32 v199, 1.0, v199, vcc
	v_mul_f32_e32 v5, v5, v199
	ds_read_b32 v184, v4 offset:896
	ds_read_b32 v185, v4 offset:832
	ds_read_b32 v186, v4 offset:768
	ds_read_b32 v187, v4 offset:704
	ds_read_b32 v188, v4 offset:640
	ds_read_b32 v189, v4 offset:576
	ds_read_b32 v190, v4 offset:512
	ds_read_b32 v191, v4 offset:448
	ds_read_b32 v192, v4 offset:384
	ds_read_b32 v193, v4 offset:320
	ds_read_b32 v194, v4 offset:256
	ds_read_b32 v195, v4 offset:192
	ds_read_b32 v196, v4 offset:128
	ds_read_b32 v197, v4 offset:64
	ds_read_b32 v198, v4
	v_cmp_gt_i32_e32 vcc, 15, v2
	s_waitcnt lgkmcnt(14)
	s_nop 1
	v_cndmask_b32_e32 v184, 1.0, v184, vcc
	v_mul_f32_e32 v5, v5, v184
	v_cmp_gt_i32_e32 vcc, 14, v2
	s_waitcnt lgkmcnt(13)
	s_nop 1
	v_cndmask_b32_e32 v185, 1.0, v185, vcc
	v_mul_f32_e32 v5, v5, v185
	v_cmp_gt_i32_e32 vcc, 13, v2
	s_waitcnt lgkmcnt(12)
	s_nop 1
	v_cndmask_b32_e32 v186, 1.0, v186, vcc
	v_mul_f32_e32 v5, v5, v186
	v_cmp_gt_i32_e32 vcc, 12, v2
	s_waitcnt lgkmcnt(11)
	s_nop 1
	v_cndmask_b32_e32 v187, 1.0, v187, vcc
	v_mul_f32_e32 v5, v5, v187
	v_cmp_gt_i32_e32 vcc, 11, v2
	s_waitcnt lgkmcnt(10)
	s_nop 1
	v_cndmask_b32_e32 v188, 1.0, v188, vcc
	v_mul_f32_e32 v5, v5, v188
	v_cmp_gt_i32_e32 vcc, 10, v2
	s_waitcnt lgkmcnt(9)
	s_nop 1
	v_cndmask_b32_e32 v189, 1.0, v189, vcc
	v_mul_f32_e32 v5, v5, v189
	v_cmp_gt_i32_e32 vcc, 9, v2
	s_waitcnt lgkmcnt(8)
	s_nop 1
	v_cndmask_b32_e32 v190, 1.0, v190, vcc
	v_mul_f32_e32 v5, v5, v190
	v_cmp_gt_i32_e32 vcc, 8, v2
	s_waitcnt lgkmcnt(7)
	s_nop 1
	v_cndmask_b32_e32 v191, 1.0, v191, vcc
	v_mul_f32_e32 v5, v5, v191
	v_cmp_gt_i32_e32 vcc, 7, v2
	s_waitcnt lgkmcnt(6)
	s_nop 1
	v_cndmask_b32_e32 v192, 1.0, v192, vcc
	v_mul_f32_e32 v5, v5, v192
	v_cmp_gt_i32_e32 vcc, 6, v2
	s_waitcnt lgkmcnt(5)
	s_nop 1
	v_cndmask_b32_e32 v193, 1.0, v193, vcc
	v_mul_f32_e32 v5, v5, v193
	v_cmp_gt_i32_e32 vcc, 5, v2
	s_waitcnt lgkmcnt(4)
	s_nop 1
	v_cndmask_b32_e32 v194, 1.0, v194, vcc
	v_mul_f32_e32 v5, v5, v194
	v_cmp_gt_i32_e32 vcc, 4, v2
	s_waitcnt lgkmcnt(3)
	s_nop 1
	v_cndmask_b32_e32 v195, 1.0, v195, vcc
	v_mul_f32_e32 v5, v5, v195
	v_cmp_gt_i32_e32 vcc, 3, v2
	s_waitcnt lgkmcnt(2)
	s_nop 1
	v_cndmask_b32_e32 v196, 1.0, v196, vcc
	v_mul_f32_e32 v5, v5, v196
	v_cmp_gt_i32_e32 vcc, 2, v2
	s_waitcnt lgkmcnt(1)
	s_nop 1
	v_cndmask_b32_e32 v197, 1.0, v197, vcc
	v_mul_f32_e32 v5, v5, v197
	v_cmp_gt_i32_e32 vcc, 1, v2
	s_waitcnt lgkmcnt(0)
	s_nop 1
	v_cndmask_b32_e32 v198, 1.0, v198, vcc
	v_mul_f32_e32 v5, v5, v198
; __device__ __forceinline__ void decode_item(Frame& F, const Args& a, int l, int item, unsigned char* ws) {
;     ...
; #pragma unroll
;         for (int j = 7; j >= 0; --j) { const int kl = sg * 8 + j; const float att = BT[kl * 16 + qh] * suf; suf *= OM[kl * 16 + qh]; BT[kl * 16 + qh] = att; }
;         if (sg == 0) ((float*)(ws + WS_TSEG))[(size_t)(sb * 64 + seg) * 16 + ((qh >> 1) & 3) * 4 + (qh & 1) * 2 + (qh >> 3)] = suf;
.LBB0_1217:
	v_lshl_or_b32 v2, v2, 9, v3
	v_add_u32_e32 v2, 0, v2
	v_add_u32_e32 v8, 0x4000, v2
	ds_read2_b32 v[6:7], v8 offset0:96 offset1:112
	ds_read_b32 v4, v2 offset:448
	v_cmp_lt_u32_e32 vcc, 15, v1
	s_waitcnt lgkmcnt(1)
	v_mul_f32_e32 v3, v5, v7
	s_waitcnt lgkmcnt(0)
	v_mul_f32_e32 v7, v5, v4
	ds_read2_b32 v[4:5], v2 offset0:80 offset1:96
	v_mul_f32_e32 v6, v7, v6
	ds_write2_b32 v8, v6, v3 offset0:96 offset1:112
	s_waitcnt lgkmcnt(1)
	v_mul_f32_e32 v5, v7, v5
	ds_read2_b32 v[6:7], v8 offset0:64 offset1:80
	s_waitcnt lgkmcnt(0)
	v_mul_f32_e32 v3, v5, v7
	v_mul_f32_e32 v7, v5, v4
	ds_read2_b32 v[4:5], v2 offset0:48 offset1:64
	v_mul_f32_e32 v6, v7, v6
	ds_write2_b32 v8, v6, v3 offset0:64 offset1:80
	s_waitcnt lgkmcnt(1)
	v_mul_f32_e32 v5, v7, v5
	ds_read2_b32 v[6:7], v8 offset0:32 offset1:48
	s_waitcnt lgkmcnt(0)
	v_mul_f32_e32 v3, v5, v7
	v_mul_f32_e32 v7, v5, v4
	ds_read2_b32 v[4:5], v2 offset0:16 offset1:32
	v_mul_f32_e32 v6, v7, v6
	ds_write2_b32 v8, v6, v3 offset0:32 offset1:48
	s_waitcnt lgkmcnt(1)
	v_mul_f32_e32 v5, v7, v5
	ds_read2_b32 v[6:7], v8 offset1:16
	v_mul_f32_e32 v3, v5, v4
	s_waitcnt lgkmcnt(0)
	v_mul_f32_e32 v7, v5, v7
	v_mul_f32_e32 v4, v3, v6
	ds_write2_b32 v8, v4, v7 offset1:16
	s_and_saveexec_b64 s[0:1], vcc
	s_xor_b64 s[0:1], exec, s[0:1]
	s_ashr_i32 s5, s4, 31
	s_or_saveexec_b64 s[0:1], s[0:1]
	v_mov_b64_e32 v[84:85], s[4:5]
	s_xor_b64 exec, exec, s[0:1]
	s_cbranch_execz .LBB0_1221
	ds_read_b32 v2, v2
	s_ashr_i32 s5, s4, 31
	s_lshl_b64 s[2:3], s[4:5], 6
	s_add_u32 s2, s10, s2
	v_lshlrev_b32_e32 v5, 3, v1
	s_addc_u32 s3, s11, s3
	v_and_b32_e32 v34, 48, v5
	s_waitcnt lgkmcnt(0)
	v_mul_f32_e32 v4, v3, v2
	v_lshl_add_u64 v[2:3], s[2:3], 0, v[34:35]
	v_and_b32_e32 v34, 8, v5
	v_lshrrev_b32_e32 v5, 1, v1
	v_lshl_add_u64 v[2:3], v[2:3], 0, v[34:35]
	v_and_b32_e32 v34, 0x7ffffffc, v5
	v_lshl_add_u64 v[2:3], v[2:3], 0, v[34:35]
	v_add_co_u32_e32 v2, vcc, 0x34b00000, v2
	v_mov_b64_e32 v[84:85], s[4:5]
	s_nop 0
	v_addc_co_u32_e32 v3, vcc, 0, v3, vcc
	global_store_dword v[2:3], v4, off
